# fast barriers additionally require gridDim == 256 (the shape the panel-ownership argument holds for)
# speedup vs baseline: 1.0015x; 1.0015x over previous
.LBB0_413:
	s_mov_b64 s[8:9], s[56:57]
	s_load_dword s1, s[8:9], 0x8c
	s_add_i32 s0, s91, 1
	s_mov_b64 s[6:7], -1
	s_waitcnt lgkmcnt(0)
	s_cmp_ge_i32 s0, s1
	s_cbranch_scc1 .LBB0_9
	s_cmp_eq_u32 s91, 0
	s_cbranch_scc1 .Lgb_full
	s_cmp_eq_u32 s91, 1
	s_cbranch_scc0 .Lchk_done
	s_load_dwordx2 s[4:5], s[56:57], 0x80
	v_and_b32_e32 v0, 63, v194
	v_lshlrev_b32_e32 v1, 2, v0
	v_and_b32_e32 v2, 7, v0
	v_lshlrev_b32_e32 v2, 2, v2
	s_waitcnt lgkmcnt(0)
	s_add_u32 s4, s4, 0x1d403800
	s_addc_u32 s5, s5, 0
	global_load_dword v3, v1, s[4:5] sc1
	global_load_dword v4, v1, s[4:5] offset:256 sc1
	global_load_dword v5, v1, s[4:5] offset:512 sc1
	global_load_dword v6, v1, s[4:5] offset:768 sc1
	global_load_dword v7, v2, s[4:5] sc1
	s_waitcnt vmcnt(0)
	v_xor_b32_e32 v3, v3, v7
	v_xor_b32_e32 v4, v4, v7
	v_xor_b32_e32 v5, v5, v7
	v_xor_b32_e32 v6, v6, v7
	v_or3_b32 v3, v3, v4, v5
	v_or_b32_e32 v3, v3, v6
	v_cmp_ne_u32_e32 vcc, 0, v3
	s_nop 1
	s_mov_b64 s[4:5], vcc
	v_cmp_eq_u32_e32 vcc, 0, v7
	s_nop 1
	s_or_b64 s[4:5], s[4:5], vcc
	s_cmp_eq_u64 s[4:5], 0
	s_cselect_b32 s4, 1, 0
	v_readlane_b32 s5, v254, 59
	s_nop 3
	s_cmpk_eq_u32 s5, 0x100
	s_cselect_b32 s4, s4, 0
	s_nop 0
	v_writelane_b32 v255, s4, 21
	s_nop 1
